# residual+LN epilogue part 1: the counted wait in front of each 8-block group now also covers that group's (gamma, beta, gate) vectors, which are issued after the X load it was derived from
# baseline (speedup 1.0000x reference)
;   __device__ __forceinline__ void operator()(f32x4 (&acc)[2][2][4][2], int pm, int pn, int wr_, int wc_, int fr_, int fq_, bf16_t* shm, int tid) const {
;     ...
;         if (stats) { lg = *(const f32x4*)(lng + col); lb = *(const f32x4*)(lnb + col); }
;         const f32x4 gv = *(const f32x4*)(g + bio + col);
; #pragma unroll
;         for (int ai = 0; ai < 2; ++ai)
; #pragma unroll
;           for (int m = 0; m < 4; ++m) {
;             const int row = pm * 256 + ai * 128 + wr * 64 + m * 16 + fr;
;             const f32x4 v = acc[ai][bj][m][n];
;             f32x4* xp = (f32x4*)(X + (long)row * DM + col);
;             f32x4 xv = *(const f32x4*)(Xr + (long)row * DM + col);
;             if (stats) { const float mu = stats[2 * row], rs = stats[2 * row + 1]; xv = (xv - mu) * rs * lg + lb; }
;             xv = xv * ALPHA + gv * v; *xp = xv;
;             acc[ai][bj][m][n] = xv;
;             s1[ai * 4 + m] += (xv[0] + xv[1]) + (xv[2] + xv[3]);
.Lres_r1_skip7:
	v_pk_mul_f32 v[178:179], v[178:179], s[92:93] op_sel_hi:[1,0]
	v_pk_mul_f32 v[180:181], v[180:181], s[92:93] op_sel_hi:[1,0]
	v_pk_fma_f32 v[34:35], v[34:35], v[236:237], v[178:179]
	v_pk_fma_f32 v[36:37], v[36:37], v[238:239], v[180:181]
	global_store_dwordx4 v224, v[34:37], s[54:55]
	global_load_dwordx4 v[178:181], v220, s[52:53] offset:512
	global_load_dwordx4 v[228:231], v146, s[46:47] offset:512
	global_load_dwordx4 v[232:235], v146, s[48:49] offset:512
	global_load_dwordx4 v[236:239], v146, s[50:51] offset:512
	s_waitcnt vmcnt(19)
	s_cbranch_vccnz .Lres_r1_skip8
	v_sub_f32_e32 v185, v185, v130
	v_sub_f32_e32 v184, v184, v130
	v_sub_f32_e32 v183, v183, v130
	v_sub_f32_e32 v182, v182, v130
	v_pk_mul_f32 v[182:183], v[182:183], v[130:131] op_sel:[0,1]
	v_pk_mul_f32 v[184:185], v[184:185], v[130:131] op_sel:[0,1]
	v_pk_fma_f32 v[182:183], v[240:241], v[182:183], v[244:245]
	v_pk_fma_f32 v[184:185], v[242:243], v[184:185], v[246:247]

;   __device__ __forceinline__ void operator()(f32x4 (&acc)[2][2][4][2], int pm, int pn, int wr_, int wc_, int fr_, int fq_, bf16_t* shm, int tid) const {
;     ...
;         if (stats) { lg = *(const f32x4*)(lng + col); lb = *(const f32x4*)(lnb + col); }
;         const f32x4 gv = *(const f32x4*)(g + bio + col);
; #pragma unroll
;         for (int ai = 0; ai < 2; ++ai)
; #pragma unroll
;           for (int m = 0; m < 4; ++m) {
;             const int row = pm * 256 + ai * 128 + wr * 64 + m * 16 + fr;
;             const f32x4 v = acc[ai][bj][m][n];
;             f32x4* xp = (f32x4*)(X + (long)row * DM + col);
;             f32x4 xv = *(const f32x4*)(Xr + (long)row * DM + col);
;             if (stats) { const float mu = stats[2 * row], rs = stats[2 * row + 1]; xv = (xv - mu) * rs * lg + lb; }
;             xv = xv * ALPHA + gv * v; *xp = xv;
;             acc[ai][bj][m][n] = xv;
;             s1[ai * 4 + m] += (xv[0] + xv[1]) + (xv[2] + xv[3]);
.Lres_r1_skip15:
	v_pk_mul_f32 v[162:163], v[162:163], s[92:93] op_sel_hi:[1,0]
	v_pk_mul_f32 v[164:165], v[164:165], s[92:93] op_sel_hi:[1,0]
	v_pk_fma_f32 v[66:67], v[66:67], v[198:199], v[162:163]
	v_pk_fma_f32 v[68:69], v[68:69], v[200:201], v[164:165]
	global_store_dwordx4 v224, v[66:69], s[54:55] offset:64
	global_load_dwordx4 v[162:165], v220, s[52:53] offset:576
	global_load_dwordx4 v[240:243], v146, s[46:47] offset:576
	global_load_dwordx4 v[244:247], v146, s[48:49] offset:576
	global_load_dwordx4 v[198:201], v146, s[50:51] offset:576
	s_waitcnt vmcnt(19)
	s_cbranch_vccnz .Lres_r1_skip16
	v_sub_f32_e32 v169, v169, v130
	v_sub_f32_e32 v168, v168, v130
	v_sub_f32_e32 v167, v167, v130
	v_sub_f32_e32 v166, v166, v130
	v_pk_mul_f32 v[166:167], v[166:167], v[130:131] op_sel:[0,1]
	v_pk_mul_f32 v[168:169], v[168:169], v[130:131] op_sel:[0,1]
	v_pk_fma_f32 v[166:167], v[228:229], v[166:167], v[232:233]
	v_pk_fma_f32 v[168:169], v[230:231], v[168:169], v[234:235]

;   __device__ __forceinline__ void operator()(f32x4 (&acc)[2][2][4][2], int pm, int pn, int wr_, int wc_, int fr_, int fq_, bf16_t* shm, int tid) const {
;     ...
;         if (stats) { lg = *(const f32x4*)(lng + col); lb = *(const f32x4*)(lnb + col); }
;         const f32x4 gv = *(const f32x4*)(g + bio + col);
; #pragma unroll
;         for (int ai = 0; ai < 2; ++ai)
; #pragma unroll
;           for (int m = 0; m < 4; ++m) {
;             const int row = pm * 256 + ai * 128 + wr * 64 + m * 16 + fr;
;             const f32x4 v = acc[ai][bj][m][n];
;             f32x4* xp = (f32x4*)(X + (long)row * DM + col);
;             f32x4 xv = *(const f32x4*)(Xr + (long)row * DM + col);
;             if (stats) { const float mu = stats[2 * row], rs = stats[2 * row + 1]; xv = (xv - mu) * rs * lg + lb; }
;             xv = xv * ALPHA + gv * v; *xp = xv;
;             acc[ai][bj][m][n] = xv;
;             s1[ai * 4 + m] += (xv[0] + xv[1]) + (xv[2] + xv[3]);
.Lres_r1_skip23:
	v_pk_mul_f32 v[194:195], v[194:195], s[92:93] op_sel_hi:[1,0]
	v_pk_mul_f32 v[196:197], v[196:197], s[92:93] op_sel_hi:[1,0]
	v_pk_fma_f32 v[102:103], v[102:103], v[236:237], v[194:195]
	v_pk_fma_f32 v[104:105], v[104:105], v[238:239], v[196:197]
	global_store_dwordx4 v224, v[102:105], s[54:55] offset:512
	s_waitcnt vmcnt(12)
	s_cbranch_vccnz .Lres_r1_skip24
	v_sub_f32_e32 v153, v153, v130
	v_sub_f32_e32 v152, v152, v130
	v_sub_f32_e32 v151, v151, v130
	v_sub_f32_e32 v150, v150, v130
	v_pk_mul_f32 v[150:151], v[150:151], v[130:131] op_sel:[0,1]
	v_pk_mul_f32 v[152:153], v[152:153], v[130:131] op_sel:[0,1]
	v_pk_fma_f32 v[150:151], v[240:241], v[150:151], v[244:245]
	v_pk_fma_f32 v[152:153], v[242:243], v[152:153], v[246:247]

;   __device__ __forceinline__ void operator()(f32x4 (&acc)[2][2][4][2], int pm, int pn, int wr_, int wc_, int fr_, int fq_, bf16_t* shm, int tid) const {
;     ...
;         if (stats) { lg = *(const f32x4*)(lng + col); lb = *(const f32x4*)(lnb + col); }
;         const f32x4 gv = *(const f32x4*)(g + bio + col);
; #pragma unroll
;         for (int ai = 0; ai < 2; ++ai)
; #pragma unroll
;           for (int m = 0; m < 4; ++m) {
;             const int row = pm * 256 + ai * 128 + wr * 64 + m * 16 + fr;
;             const f32x4 v = acc[ai][bj][m][n];
;             f32x4* xp = (f32x4*)(X + (long)row * DM + col);
;             f32x4 xv = *(const f32x4*)(Xr + (long)row * DM + col);
;             if (stats) { const float mu = stats[2 * row], rs = stats[2 * row + 1]; xv = (xv - mu) * rs * lg + lb; }
;             xv = xv * ALPHA + gv * v; *xp = xv;
;             acc[ai][bj][m][n] = xv;
;             s1[ai * 4 + m] += (xv[0] + xv[1]) + (xv[2] + xv[3]);
.Lres_r2_skip7:
	v_pk_mul_f32 v[178:179], v[178:179], s[92:93] op_sel_hi:[1,0]
	v_pk_mul_f32 v[180:181], v[180:181], s[92:93] op_sel_hi:[1,0]
	v_pk_fma_f32 v[54:55], v[54:55], v[206:207], v[178:179]
	v_pk_fma_f32 v[56:57], v[56:57], v[208:209], v[180:181]
	global_store_dwordx4 v245, v[54:57], s[54:55]
	global_load_dwordx4 v[178:181], v225, s[52:53] offset:512
	global_load_dwordx4 v[198:201], v146, s[46:47] offset:512
	global_load_dwordx4 v[202:205], v146, s[48:49] offset:512
	global_load_dwordx4 v[206:209], v146, s[50:51] offset:512
	s_waitcnt vmcnt(19)
	s_cbranch_vccnz .Lres_r2_skip8
	v_sub_f32_e32 v185, v185, v130
	v_sub_f32_e32 v184, v184, v130
	v_sub_f32_e32 v183, v183, v130
	v_sub_f32_e32 v182, v182, v130
	v_pk_mul_f32 v[182:183], v[182:183], v[130:131] op_sel:[0,1]
	v_pk_mul_f32 v[184:185], v[184:185], v[130:131] op_sel:[0,1]
	v_pk_fma_f32 v[182:183], v[210:211], v[182:183], v[214:215]
	v_pk_fma_f32 v[184:185], v[212:213], v[184:185], v[216:217]

;   __device__ __forceinline__ void operator()(f32x4 (&acc)[2][2][4][2], int pm, int pn, int wr_, int wc_, int fr_, int fq_, bf16_t* shm, int tid) const {
;     ...
;         if (stats) { lg = *(const f32x4*)(lng + col); lb = *(const f32x4*)(lnb + col); }
;         const f32x4 gv = *(const f32x4*)(g + bio + col);
; #pragma unroll
;         for (int ai = 0; ai < 2; ++ai)
; #pragma unroll
;           for (int m = 0; m < 4; ++m) {
;             const int row = pm * 256 + ai * 128 + wr * 64 + m * 16 + fr;
;             const f32x4 v = acc[ai][bj][m][n];
;             f32x4* xp = (f32x4*)(X + (long)row * DM + col);
;             f32x4 xv = *(const f32x4*)(Xr + (long)row * DM + col);
;             if (stats) { const float mu = stats[2 * row], rs = stats[2 * row + 1]; xv = (xv - mu) * rs * lg + lb; }
;             xv = xv * ALPHA + gv * v; *xp = xv;
;             acc[ai][bj][m][n] = xv;
;             s1[ai * 4 + m] += (xv[0] + xv[1]) + (xv[2] + xv[3]);
.Lres_r2_skip15:
	v_pk_mul_f32 v[162:163], v[162:163], s[92:93] op_sel_hi:[1,0]
	v_pk_mul_f32 v[164:165], v[164:165], s[92:93] op_sel_hi:[1,0]
	v_pk_fma_f32 v[66:67], v[66:67], v[228:229], v[162:163]
	v_pk_fma_f32 v[68:69], v[68:69], v[230:231], v[164:165]
	global_store_dwordx4 v245, v[66:69], s[54:55] offset:64
	global_load_dwordx4 v[162:165], v225, s[52:53] offset:576
	global_load_dwordx4 v[210:213], v146, s[46:47] offset:576
	global_load_dwordx4 v[214:217], v146, s[48:49] offset:576
	global_load_dwordx4 v[228:231], v146, s[50:51] offset:576
	s_waitcnt vmcnt(19)
	s_cbranch_vccnz .Lres_r2_skip16
	v_sub_f32_e32 v169, v169, v130
	v_sub_f32_e32 v168, v168, v130
	v_sub_f32_e32 v167, v167, v130
	v_sub_f32_e32 v166, v166, v130
	v_pk_mul_f32 v[166:167], v[166:167], v[130:131] op_sel:[0,1]
	v_pk_mul_f32 v[168:169], v[168:169], v[130:131] op_sel:[0,1]
	v_pk_fma_f32 v[166:167], v[198:199], v[166:167], v[202:203]
	v_pk_fma_f32 v[168:169], v[200:201], v[168:169], v[204:205]

;   __device__ __forceinline__ void operator()(f32x4 (&acc)[2][2][4][2], int pm, int pn, int wr_, int wc_, int fr_, int fq_, bf16_t* shm, int tid) const {
;     ...
;         if (stats) { lg = *(const f32x4*)(lng + col); lb = *(const f32x4*)(lnb + col); }
;         const f32x4 gv = *(const f32x4*)(g + bio + col);
; #pragma unroll
;         for (int ai = 0; ai < 2; ++ai)
; #pragma unroll
;           for (int m = 0; m < 4; ++m) {
;             const int row = pm * 256 + ai * 128 + wr * 64 + m * 16 + fr;
;             const f32x4 v = acc[ai][bj][m][n];
;             f32x4* xp = (f32x4*)(X + (long)row * DM + col);
;             f32x4 xv = *(const f32x4*)(Xr + (long)row * DM + col);
;             if (stats) { const float mu = stats[2 * row], rs = stats[2 * row + 1]; xv = (xv - mu) * rs * lg + lb; }
;             xv = xv * ALPHA + gv * v; *xp = xv;
;             acc[ai][bj][m][n] = xv;
;             s1[ai * 4 + m] += (xv[0] + xv[1]) + (xv[2] + xv[3]);
.Lres_r2_skip23:
	v_pk_mul_f32 v[194:195], v[194:195], s[92:93] op_sel_hi:[1,0]
	v_pk_mul_f32 v[196:197], v[196:197], s[92:93] op_sel_hi:[1,0]
	v_pk_fma_f32 v[74:75], v[74:75], v[206:207], v[194:195]
	v_pk_fma_f32 v[76:77], v[76:77], v[208:209], v[196:197]
	global_store_dwordx4 v245, v[74:77], s[54:55] offset:512
	s_waitcnt vmcnt(12)
	s_cbranch_vccnz .Lres_r2_skip24
	v_sub_f32_e32 v153, v153, v130
	v_sub_f32_e32 v152, v152, v130
	v_sub_f32_e32 v151, v151, v130
	v_sub_f32_e32 v150, v150, v130
	v_pk_mul_f32 v[150:151], v[150:151], v[130:131] op_sel:[0,1]
	v_pk_mul_f32 v[152:153], v[152:153], v[130:131] op_sel:[0,1]
	v_pk_fma_f32 v[150:151], v[210:211], v[150:151], v[214:215]
	v_pk_fma_f32 v[152:153], v[212:213], v[152:153], v[216:217]
